# prefetch DMAs moved behind the 6-load stage groups (one more phase of latency tolerance), waits recounted 8/9/9/9 and 9/10/9/10, stand-in DMA before the out-proj loop
# speedup vs baseline: 1.0405x; 1.0074x over previous
; #define PG8_STAGE(bufoff, gbase, voff) do { _Pragma("unroll") for (int _i = 0; _i < 2; ++_i) \
;         __builtin_amdgcn_global_load_lds((const unsigned*)((const char*)(gbase) + (voff)[_i]), (LAS unsigned*)(lds + (bufoff) + ldsw + _i * 8192), 16, 0, 0); } while (0)
; #define PG8_LDA(dst, b, h) do { _Pragma("unroll") for (int m = 0; m < 4; ++m) _Pragma("unroll") for (int k = 0; k < 2; ++k) dst[m][k] = *(const LAS bf16x8*)(lds + PG8_SA(b, h) + aoff + m * 2048 + k * 1024); } while (0)
; #define PG8_LDB(dst, b, h) do { _Pragma("unroll") for (int n = 0; n < 2; ++n) _Pragma("unroll") for (int k = 0; k < 2; ++k) dst[n][k] = *(const LAS bf16x8*)(lds + PG8_SB(b, h) + boff + n * 2048 + k * 1024); } while (0)
; #define PG8_MMA(ai, bj, At, Bt) do { __builtin_amdgcn_s_setprio(1); _Pragma("unroll") for (int m = 0; m < 4; ++m) _Pragma("unroll") for (int n = 0; n < 2; ++n) _Pragma("unroll") for (int k = 0; k < 2; ++k) \
;         acc[ai][bj][m][n] = __builtin_amdgcn_mfma_f32_16x16x32_bf16(Bt[n][k], At[m][k], acc[ai][bj][m][n], 0, 0, 0); __builtin_amdgcn_s_setprio(0); } while (0)
; #define PG8_WAIT_V(n) asm volatile("s_waitcnt vmcnt(" #n ")" ::: "memory")
; template <class Epi, bool ALIGN_EPI>
; __device__ __forceinline__ void gemm_phase(LAS unsigned char* lds, const Gemm g, int G, int cid, const Epi& E) {
;     ...
;         const bool has_next = S.next(ui + 1, nxt);
;         const char* nA = has_next ? tileA(g, nxt) : cA; const char* nB = has_next ? tileB(g, nxt) : cB;
;         for (int t = 0; t < nt; t += 2) {
;             const bool last = (t == nt - 2);
;             const char* a1 = cA + (size_t)(t + 1) * kA;
;             const char* a2 = last ? nA : cA + (size_t)(t + 2) * kA; const char* b2 = last ? nB : cB + (size_t)(t + 2) * kB;
;             const char* a3 = a2 + kA; const char* b3 = b2 + kB;
;             PG8_LDB(B0, 0, 0); PG8_LDB(B1, 0, 1); PG8_SCHED; PG8_LDA(At, 0, 0); PG8_STAGE(PG8_SA(1, 1), a1 + hA, voffA);
;             PG8_WAIT_V(8); PG8_WAIT_L(0); PG8_BAR; PG8_MMA(0, 0, At, B0); PG8_MMA(0, 1, At, B1); PG8_BAR; PG8_SCHED;
;     ...
; #pragma unroll
;         for (int a = 0; a < 2; ++a)
; #pragma unroll
;             for (int b = 0; b < 2; ++b)
; #pragma unroll
;                 for (int m = 0; m < 4; ++m)
; #pragma unroll
;                     for (int n = 0; n < 2; ++n) acc[a][b][m][n] = (f32x4){0.f, 0.f, 0.f, 0.f};
;         cur = nxt; cA = nA; cB = nB; ++ui;
.LBB0_726:
	s_and_b32 s30, s72, 0x7fffffff
	s_lshl_b64 s[44:45], s[30:31], 14
	s_add_u32 s44, s1, s44
	s_addc_u32 s45, s24, s45
	s_and_b64 s[42:43], s[42:43], exec
	s_cselect_b32 s30, s45, s49
	s_cselect_b32 s74, s44, s48
	s_add_u32 s75, s48, 0x80000
	v_mov_b32_e32 v0, 0
	s_addc_u32 s76, s49, 0
	s_mov_b32 s77, -2
	s_waitcnt lgkmcnt(0)
	v_mov_b32_e32 v1, v0
	v_mov_b32_e32 v2, v0
	v_mov_b32_e32 v3, v0
	v_mov_b32_e32 v4, v0
	v_mov_b32_e32 v5, v0
	v_mov_b32_e32 v6, v0
	v_mov_b32_e32 v7, v0
	v_mov_b32_e32 v16, v0
	v_mov_b32_e32 v17, v0
	v_mov_b32_e32 v18, v0
	v_mov_b32_e32 v19, v0
	v_mov_b32_e32 v20, v0
	v_mov_b32_e32 v21, v0
	v_mov_b32_e32 v22, v0
	v_mov_b32_e32 v23, v0
	v_mov_b32_e32 v32, v0
	v_mov_b32_e32 v33, v0
	v_mov_b32_e32 v34, v0
	v_mov_b32_e32 v35, v0
	v_mov_b32_e32 v36, v0
	v_mov_b32_e32 v37, v0
	v_mov_b32_e32 v38, v0
	v_mov_b32_e32 v39, v0
	v_mov_b32_e32 v48, v0
	v_mov_b32_e32 v49, v0
	v_mov_b32_e32 v50, v0
	v_mov_b32_e32 v51, v0
	v_mov_b32_e32 v52, v0
	v_mov_b32_e32 v53, v0
	v_mov_b32_e32 v54, v0
	v_mov_b32_e32 v55, v0
	v_mov_b32_e32 v8, v0
	v_mov_b32_e32 v9, v0
	v_mov_b32_e32 v10, v0
	v_mov_b32_e32 v11, v0
	v_mov_b32_e32 v12, v0
	v_mov_b32_e32 v13, v0
	v_mov_b32_e32 v14, v0
	v_mov_b32_e32 v15, v0
	v_mov_b32_e32 v24, v0
	v_mov_b32_e32 v25, v0
	v_mov_b32_e32 v26, v0
	v_mov_b32_e32 v27, v0
	v_mov_b32_e32 v28, v0
	v_mov_b32_e32 v29, v0
	v_mov_b32_e32 v30, v0
	v_mov_b32_e32 v31, v0
	v_mov_b32_e32 v40, v0
	v_mov_b32_e32 v41, v0
	v_mov_b32_e32 v42, v0
	v_mov_b32_e32 v43, v0
	v_mov_b32_e32 v44, v0
	v_mov_b32_e32 v45, v0
	v_mov_b32_e32 v46, v0
	v_mov_b32_e32 v47, v0
	v_mov_b32_e32 v56, v0
	v_mov_b32_e32 v57, v0
	v_mov_b32_e32 v58, v0
	v_mov_b32_e32 v59, v0
	v_mov_b32_e32 v60, v0
	v_mov_b32_e32 v61, v0
	v_mov_b32_e32 v62, v0
	v_mov_b32_e32 v63, v0
	v_mov_b32_e32 v64, v0
	v_mov_b32_e32 v65, v0
	v_mov_b32_e32 v66, v0
	v_mov_b32_e32 v67, v0
	v_mov_b32_e32 v68, v0
	v_mov_b32_e32 v69, v0
	v_mov_b32_e32 v70, v0
	v_mov_b32_e32 v71, v0
	v_mov_b32_e32 v80, v0
	v_mov_b32_e32 v81, v0
	v_mov_b32_e32 v82, v0
	v_mov_b32_e32 v83, v0
	v_mov_b32_e32 v84, v0
	v_mov_b32_e32 v85, v0
	v_mov_b32_e32 v86, v0
	v_mov_b32_e32 v87, v0
	v_mov_b32_e32 v96, v0
	v_mov_b32_e32 v97, v0
	v_mov_b32_e32 v98, v0
	v_mov_b32_e32 v99, v0
	v_mov_b32_e32 v100, v0
	v_mov_b32_e32 v101, v0
	v_mov_b32_e32 v102, v0
	v_mov_b32_e32 v103, v0
	v_mov_b32_e32 v120, v0
	v_mov_b32_e32 v121, v0
	v_mov_b32_e32 v122, v0
	v_mov_b32_e32 v123, v0
	v_mov_b32_e32 v124, v0
	v_mov_b32_e32 v125, v0
	v_mov_b32_e32 v126, v0
	v_mov_b32_e32 v127, v0
	v_mov_b32_e32 v72, v0
	v_mov_b32_e32 v73, v0
	v_mov_b32_e32 v74, v0
	v_mov_b32_e32 v75, v0
	v_mov_b32_e32 v76, v0
	v_mov_b32_e32 v77, v0
	v_mov_b32_e32 v78, v0
	v_mov_b32_e32 v79, v0
	v_mov_b32_e32 v88, v0
	v_mov_b32_e32 v89, v0
	v_mov_b32_e32 v90, v0
	v_mov_b32_e32 v91, v0
	v_mov_b32_e32 v92, v0
	v_mov_b32_e32 v93, v0
	v_mov_b32_e32 v94, v0
	v_mov_b32_e32 v95, v0
	v_mov_b32_e32 v104, v0
	v_mov_b32_e32 v105, v0
	v_mov_b32_e32 v106, v0
	v_mov_b32_e32 v107, v0
	v_mov_b32_e32 v108, v0
	v_mov_b32_e32 v109, v0
	v_mov_b32_e32 v110, v0
	v_mov_b32_e32 v111, v0
	s_waitcnt vmcnt(0)
	v_mov_b32_e32 v148, v0
	v_mov_b32_e32 v149, v0
	v_mov_b32_e32 v150, v0
	v_mov_b32_e32 v151, v0
	v_mov_b32_e32 v152, v0
	v_mov_b32_e32 v153, v0
	v_mov_b32_e32 v154, v0
	v_mov_b32_e32 v155, v0
	v_mbcnt_lo_u32_b32 v224, -1, 0
	v_mbcnt_hi_u32_b32 v224, -1, v224
	v_lshlrev_b32_e32 v224, 4, v224
	s_mov_b32 m0, 0x22c00
	s_nop 0
	global_load_lds_dwordx4 v224, s[22:23]
.LBB0_727:
	s_add_u32 s42, s46, 0x100
	s_addc_u32 s43, s47, 0
	s_add_i32 s6, 0, 0x10000
	s_cmp_eq_u32 s77, 28
	s_cselect_b32 s51, s29, s43
	s_cselect_b32 s50, s28, s42
	s_cselect_b32 s49, s30, s76
	s_cselect_b32 s48, s74, s75
	s_add_i32 s7, 0, 0x14000
	v_add_u32_e32 v132, s6, v220
	v_add_u32_e32 v160, s7, v220
	ds_read_b128 v[112:115], v132
	ds_read_b128 v[116:119], v132 offset:1024
	ds_read_b128 v[128:131], v132 offset:2048
	ds_read_b128 v[132:135], v132 offset:3072
	ds_read_b128 v[140:143], v160
	ds_read_b128 v[144:147], v160 offset:1024
	ds_read_b128 v[156:159], v160 offset:2048
	ds_read_b128 v[160:163], v160 offset:3072
	v_lshl_add_u64 v[198:199], s[46:47], 0, v[184:185]
	s_add_i32 m0, s52, 0xc000
	ds_read_b128 v[164:167], v222
	ds_read_b128 v[168:171], v222 offset:1024
	ds_read_b128 v[172:175], v222 offset:2048
	ds_read_b128 v[176:179], v222 offset:3072
	ds_read_b128 v[188:191], v222 offset:4096
	ds_read_b128 v[206:209], v222 offset:5120
	ds_read_b128 v[210:213], v222 offset:6144
	ds_read_b128 v[214:217], v222 offset:7168
	global_load_lds_dwordx4 v[198:199], off
	v_lshl_add_u64 v[198:199], s[46:47], 0, v[186:187]
	s_add_i32 m0, s52, 0xe000
	s_nop 0
	global_load_lds_dwordx4 v[198:199], off
	s_waitcnt vmcnt(9)
	s_waitcnt lgkmcnt(0)
	s_barrier
; #define PG8_STAGE(bufoff, gbase, voff) do { _Pragma("unroll") for (int _i = 0; _i < 2; ++_i) \
;         __builtin_amdgcn_global_load_lds((const unsigned*)((const char*)(gbase) + (voff)[_i]), (LAS unsigned*)(lds + (bufoff) + ldsw + _i * 8192), 16, 0, 0); } while (0)
; #define PG8_LDA(dst, b, h) do { _Pragma("unroll") for (int m = 0; m < 4; ++m) _Pragma("unroll") for (int k = 0; k < 2; ++k) dst[m][k] = *(const LAS bf16x8*)(lds + PG8_SA(b, h) + aoff + m * 2048 + k * 1024); } while (0)
; #define PG8_LDB(dst, b, h) do { _Pragma("unroll") for (int n = 0; n < 2; ++n) _Pragma("unroll") for (int k = 0; k < 2; ++k) dst[n][k] = *(const LAS bf16x8*)(lds + PG8_SB(b, h) + boff + n * 2048 + k * 1024); } while (0)
; #define PG8_MMA(ai, bj, At, Bt) do { __builtin_amdgcn_s_setprio(1); _Pragma("unroll") for (int m = 0; m < 4; ++m) _Pragma("unroll") for (int n = 0; n < 2; ++n) _Pragma("unroll") for (int k = 0; k < 2; ++k) \
;         acc[ai][bj][m][n] = __builtin_amdgcn_mfma_f32_16x16x32_bf16(Bt[n][k], At[m][k], acc[ai][bj][m][n], 0, 0, 0); __builtin_amdgcn_s_setprio(0); } while (0)
; #define PG8_WAIT_V(n) asm volatile("s_waitcnt vmcnt(" #n ")" ::: "memory")
; #define PG8_WAIT_L(n) asm volatile("s_waitcnt lgkmcnt(" #n ")" ::: "memory")
; #define PG8_BAR __builtin_amdgcn_s_barrier()
; #define PG8_SCHED __builtin_amdgcn_sched_barrier(0)
; template <class Epi, bool ALIGN_EPI>
; __device__ __forceinline__ void gemm_phase(LAS unsigned char* lds, const Gemm g, int G, int cid, const Epi& E) {
;     ...
;             PG8_WAIT_V(8); PG8_WAIT_L(0); PG8_BAR; PG8_MMA(0, 0, At, B0); PG8_MMA(0, 1, At, B1); PG8_BAR; PG8_SCHED;
;             PG8_LDA(At, 0, 1); PG8_STAGE(PG8_SB(0, 0), b2, voffB); PG8_STAGE(PG8_SB(0, 1), b2 + hB, voffB); PG8_STAGE(PG8_SA(0, 0), a2, voffA);
;             PG8_WAIT_V(8); PG8_WAIT_L(0); PG8_BAR; PG8_MMA(1, 0, At, B0); PG8_MMA(1, 1, At, B1); PG8_BAR; PG8_SCHED;
;             PG8_LDB(B0, 1, 0); PG8_LDB(B1, 1, 1); PG8_SCHED; PG8_LDA(At, 1, 0); PG8_STAGE(PG8_SA(0, 1), a2 + hA, voffA);
;             PG8_WAIT_V(8); PG8_WAIT_L(0); PG8_BAR; PG8_MMA(0, 0, At, B0); PG8_MMA(0, 1, At, B1); PG8_BAR; PG8_SCHED;
	s_setprio 1
	s_waitcnt lgkmcnt(0)
	v_mfma_f32_16x16x32_bf16 v[152:155], v[112:115], v[164:167], v[152:155]
	v_mfma_f32_16x16x32_bf16 v[148:151], v[128:131], v[164:167], v[148:151]
	v_mfma_f32_16x16x32_bf16 v[108:111], v[112:115], v[172:175], v[108:111]
	v_mfma_f32_16x16x32_bf16 v[104:107], v[128:131], v[172:175], v[104:107]
	v_mfma_f32_16x16x32_bf16 v[92:95], v[112:115], v[188:191], v[92:95]
	v_mfma_f32_16x16x32_bf16 v[88:91], v[128:131], v[188:191], v[88:91]
	v_mfma_f32_16x16x32_bf16 v[76:79], v[112:115], v[210:213], v[76:79]
	v_mfma_f32_16x16x32_bf16 v[72:75], v[128:131], v[210:213], v[72:75]
	v_mfma_f32_16x16x32_bf16 v[152:155], v[116:119], v[168:171], v[152:155]
	v_mfma_f32_16x16x32_bf16 v[148:151], v[132:135], v[168:171], v[148:151]
	v_mfma_f32_16x16x32_bf16 v[108:111], v[116:119], v[176:179], v[108:111]
	v_mfma_f32_16x16x32_bf16 v[104:107], v[132:135], v[176:179], v[104:107]
	v_mfma_f32_16x16x32_bf16 v[92:95], v[116:119], v[206:209], v[92:95]
	v_mfma_f32_16x16x32_bf16 v[88:91], v[132:135], v[206:209], v[88:91]
	v_mfma_f32_16x16x32_bf16 v[76:79], v[116:119], v[214:217], v[76:79]
	v_mfma_f32_16x16x32_bf16 v[72:75], v[132:135], v[214:217], v[72:75]
	s_setprio 0
	s_setprio 1
	v_mfma_f32_16x16x32_bf16 v[124:127], v[140:143], v[164:167], v[124:127]
	v_mfma_f32_16x16x32_bf16 v[120:123], v[156:159], v[164:167], v[120:123]
	v_mfma_f32_16x16x32_bf16 v[100:103], v[140:143], v[172:175], v[100:103]
	v_mfma_f32_16x16x32_bf16 v[96:99], v[156:159], v[172:175], v[96:99]
	v_mfma_f32_16x16x32_bf16 v[84:87], v[140:143], v[188:191], v[84:87]
	v_mfma_f32_16x16x32_bf16 v[80:83], v[156:159], v[188:191], v[80:83]
	v_mfma_f32_16x16x32_bf16 v[68:71], v[140:143], v[210:213], v[68:71]
	v_mfma_f32_16x16x32_bf16 v[64:67], v[156:159], v[210:213], v[64:67]
	v_mfma_f32_16x16x32_bf16 v[124:127], v[144:147], v[168:171], v[124:127]
	v_mfma_f32_16x16x32_bf16 v[120:123], v[160:163], v[168:171], v[120:123]
	v_mfma_f32_16x16x32_bf16 v[100:103], v[144:147], v[176:179], v[100:103]
	v_mfma_f32_16x16x32_bf16 v[96:99], v[160:163], v[176:179], v[96:99]
	v_mfma_f32_16x16x32_bf16 v[84:87], v[144:147], v[206:209], v[84:87]
	v_mfma_f32_16x16x32_bf16 v[80:83], v[160:163], v[206:209], v[80:83]
	v_mfma_f32_16x16x32_bf16 v[68:71], v[144:147], v[214:217], v[68:71]
	v_mfma_f32_16x16x32_bf16 v[64:67], v[160:163], v[214:217], v[64:67]
	s_setprio 0
	s_barrier
	s_add_i32 s6, s6, s25
	v_lshl_add_u64 v[198:199], s[48:49], 0, v[138:139]
	s_mov_b32 m0, s6
	ds_read_b128 v[164:167], v222 offset:16384
	ds_read_b128 v[168:171], v222 offset:17408
	ds_read_b128 v[172:175], v222 offset:18432
	ds_read_b128 v[176:179], v222 offset:19456
	ds_read_b128 v[188:191], v222 offset:20480
	ds_read_b128 v[206:209], v222 offset:21504
	ds_read_b128 v[210:213], v222 offset:22528
	ds_read_b128 v[214:217], v222 offset:23552
	global_load_lds_dwordx4 v[198:199], off
	s_add_i32 m0, s6, 0x2000
	s_add_u32 s46, s48, 0x2000
	v_lshl_add_u64 v[198:199], s[48:49], 0, v[136:137]
	s_addc_u32 s47, s49, 0
	s_add_i32 s6, s7, s25
	global_load_lds_dwordx4 v[198:199], off
	v_lshl_add_u64 v[198:199], s[46:47], 0, v[138:139]
	s_mov_b32 m0, s6
	v_lshl_add_u64 v[200:201], s[50:51], 0, v[180:181]
	global_load_lds_dwordx4 v[198:199], off
	v_lshl_add_u64 v[198:199], s[46:47], 0, v[136:137]
	s_add_i32 m0, s6, 0x2000
	s_nop 0
	global_load_lds_dwordx4 v[198:199], off
	v_lshl_add_u64 v[198:199], s[50:51], 0, v[182:183]
	s_mov_b32 m0, s52
	s_nop 0
	global_load_lds_dwordx4 v[198:199], off
	s_mov_b32 m0, s53
	s_nop 0
	global_load_lds_dwordx4 v[200:201], off
	s_add_i32 vcc_lo, s77, 2
	s_lshl_b32 vcc_lo, vcc_lo, 16
	s_lshl_b32 vcc_hi, s13, 21
	s_add_i32 vcc_lo, vcc_lo, vcc_hi
	s_lshl_b32 vcc_hi, s25, 4
	s_add_i32 vcc_lo, vcc_lo, vcc_hi
	s_lshl_b32 vcc_hi, s12, 10
	s_add_i32 vcc_lo, vcc_lo, vcc_hi
	s_add_u32 vcc_lo, s22, vcc_lo
	s_addc_u32 vcc_hi, s23, 0
	s_mov_b32 m0, 0x22c00
	s_nop 0
	global_load_lds_dwordx4 v224, vcc
	s_waitcnt vmcnt(10)
	s_waitcnt lgkmcnt(0)
	s_barrier
	s_setprio 1
	s_waitcnt lgkmcnt(0)
	v_mfma_f32_16x16x32_bf16 v[60:63], v[112:115], v[164:167], v[60:63]
	v_mfma_f32_16x16x32_bf16 v[56:59], v[128:131], v[164:167], v[56:59]
	v_mfma_f32_16x16x32_bf16 v[44:47], v[112:115], v[172:175], v[44:47]
	v_mfma_f32_16x16x32_bf16 v[40:43], v[128:131], v[172:175], v[40:43]
	v_mfma_f32_16x16x32_bf16 v[28:31], v[112:115], v[188:191], v[28:31]
	v_mfma_f32_16x16x32_bf16 v[24:27], v[128:131], v[188:191], v[24:27]
	v_mfma_f32_16x16x32_bf16 v[12:15], v[112:115], v[210:213], v[12:15]
	v_mfma_f32_16x16x32_bf16 v[8:11], v[128:131], v[210:213], v[8:11]
	v_mfma_f32_16x16x32_bf16 v[60:63], v[116:119], v[168:171], v[60:63]
	v_mfma_f32_16x16x32_bf16 v[56:59], v[132:135], v[168:171], v[56:59]
	v_mfma_f32_16x16x32_bf16 v[44:47], v[116:119], v[176:179], v[44:47]
	v_mfma_f32_16x16x32_bf16 v[40:43], v[132:135], v[176:179], v[40:43]
	v_mfma_f32_16x16x32_bf16 v[28:31], v[116:119], v[206:209], v[28:31]
	v_mfma_f32_16x16x32_bf16 v[24:27], v[132:135], v[206:209], v[24:27]
	v_mfma_f32_16x16x32_bf16 v[12:15], v[116:119], v[214:217], v[12:15]
	v_mfma_f32_16x16x32_bf16 v[8:11], v[132:135], v[214:217], v[8:11]
	s_setprio 0
	s_setprio 1
	v_mfma_f32_16x16x32_bf16 v[52:55], v[140:143], v[164:167], v[52:55]
	v_mfma_f32_16x16x32_bf16 v[48:51], v[156:159], v[164:167], v[48:51]
	v_mfma_f32_16x16x32_bf16 v[36:39], v[140:143], v[172:175], v[36:39]
	v_mfma_f32_16x16x32_bf16 v[32:35], v[156:159], v[172:175], v[32:35]
	v_mfma_f32_16x16x32_bf16 v[20:23], v[140:143], v[188:191], v[20:23]
	v_mfma_f32_16x16x32_bf16 v[16:19], v[156:159], v[188:191], v[16:19]
	v_mfma_f32_16x16x32_bf16 v[4:7], v[140:143], v[210:213], v[4:7]
	v_mfma_f32_16x16x32_bf16 v[0:3], v[156:159], v[210:213], v[0:3]
	v_mfma_f32_16x16x32_bf16 v[52:55], v[144:147], v[168:171], v[52:55]
	v_mfma_f32_16x16x32_bf16 v[48:51], v[160:163], v[168:171], v[48:51]
	v_mfma_f32_16x16x32_bf16 v[36:39], v[144:147], v[176:179], v[36:39]
	v_mfma_f32_16x16x32_bf16 v[32:35], v[160:163], v[176:179], v[32:35]
	v_mfma_f32_16x16x32_bf16 v[20:23], v[144:147], v[206:209], v[20:23]
	v_mfma_f32_16x16x32_bf16 v[16:19], v[160:163], v[206:209], v[16:19]
	v_mfma_f32_16x16x32_bf16 v[4:7], v[144:147], v[214:217], v[4:7]
	v_mfma_f32_16x16x32_bf16 v[0:3], v[160:163], v[214:217], v[0:3]
	s_setprio 0
	s_barrier
; #define PG8_STAGE(bufoff, gbase, voff) do { _Pragma("unroll") for (int _i = 0; _i < 2; ++_i) \
;         __builtin_amdgcn_global_load_lds((const unsigned*)((const char*)(gbase) + (voff)[_i]), (LAS unsigned*)(lds + (bufoff) + ldsw + _i * 8192), 16, 0, 0); } while (0)
; #define PG8_LDA(dst, b, h) do { _Pragma("unroll") for (int m = 0; m < 4; ++m) _Pragma("unroll") for (int k = 0; k < 2; ++k) dst[m][k] = *(const LAS bf16x8*)(lds + PG8_SA(b, h) + aoff + m * 2048 + k * 1024); } while (0)
; #define PG8_LDB(dst, b, h) do { _Pragma("unroll") for (int n = 0; n < 2; ++n) _Pragma("unroll") for (int k = 0; k < 2; ++k) dst[n][k] = *(const LAS bf16x8*)(lds + PG8_SB(b, h) + boff + n * 2048 + k * 1024); } while (0)
; #define PG8_MMA(ai, bj, At, Bt) do { __builtin_amdgcn_s_setprio(1); _Pragma("unroll") for (int m = 0; m < 4; ++m) _Pragma("unroll") for (int n = 0; n < 2; ++n) _Pragma("unroll") for (int k = 0; k < 2; ++k) \
;         acc[ai][bj][m][n] = __builtin_amdgcn_mfma_f32_16x16x32_bf16(Bt[n][k], At[m][k], acc[ai][bj][m][n], 0, 0, 0); __builtin_amdgcn_s_setprio(0); } while (0)
; #define PG8_WAIT_V(n) asm volatile("s_waitcnt vmcnt(" #n ")" ::: "memory")
; #define PG8_WAIT_L(n) asm volatile("s_waitcnt lgkmcnt(" #n ")" ::: "memory")
; #define PG8_BAR __builtin_amdgcn_s_barrier()
; #define PG8_SCHED __builtin_amdgcn_sched_barrier(0)
; template <class Epi, bool ALIGN_EPI>
; __device__ __forceinline__ void gemm_phase(LAS unsigned char* lds, const Gemm g, int G, int cid, const Epi& E) {
;     ...
;             PG8_LDB(B0, 1, 0); PG8_LDB(B1, 1, 1); PG8_SCHED; PG8_LDA(At, 1, 0); PG8_STAGE(PG8_SA(0, 1), a2 + hA, voffA);
;             PG8_WAIT_V(8); PG8_WAIT_L(0); PG8_BAR; PG8_MMA(0, 0, At, B0); PG8_MMA(0, 1, At, B1); PG8_BAR; PG8_SCHED;
;             PG8_LDA(At, 1, 1); PG8_STAGE(PG8_SB(1, 0), b3, voffB); PG8_STAGE(PG8_SB(1, 1), b3 + hB, voffB); PG8_STAGE(PG8_SA(1, 0), a3, voffA);
	s_add_i32 s6, 0, 0x18000
	s_add_i32 s7, 0, 0x1c000
	v_add_u32_e32 v132, s6, v220
	v_add_u32_e32 v160, s7, v220
	ds_read_b128 v[112:115], v132
	ds_read_b128 v[116:119], v132 offset:1024
	ds_read_b128 v[128:131], v132 offset:2048
	ds_read_b128 v[132:135], v132 offset:3072
	ds_read_b128 v[140:143], v160
	ds_read_b128 v[144:147], v160 offset:1024
	ds_read_b128 v[156:159], v160 offset:2048
	ds_read_b128 v[160:163], v160 offset:3072
	s_add_u32 s46, s50, 0x84000
	s_addc_u32 s47, s51, 0
	s_mov_b32 m0, s54
	v_lshl_add_u64 v[218:219], s[46:47], 0, v[182:183]
	ds_read_b128 v[164:167], v222 offset:32768
	ds_read_b128 v[168:171], v222 offset:33792
	ds_read_b128 v[172:175], v222 offset:34816
	ds_read_b128 v[176:179], v222 offset:35840
	ds_read_b128 v[188:191], v222 offset:36864
	ds_read_b128 v[206:209], v222 offset:37888
	ds_read_b128 v[210:213], v222 offset:38912
	ds_read_b128 v[214:217], v222 offset:39936
	global_load_lds_dwordx4 v[218:219], off
	v_lshl_add_u64 v[218:219], s[46:47], 0, v[180:181]
	s_mov_b32 m0, s55
	s_nop 0
	global_load_lds_dwordx4 v[218:219], off
	s_waitcnt vmcnt(9)
	s_waitcnt lgkmcnt(0)
	s_barrier
	s_setprio 1
	s_waitcnt lgkmcnt(0)
	v_mfma_f32_16x16x32_bf16 v[152:155], v[112:115], v[164:167], v[152:155]
	v_mfma_f32_16x16x32_bf16 v[148:151], v[128:131], v[164:167], v[148:151]
	v_mfma_f32_16x16x32_bf16 v[108:111], v[112:115], v[172:175], v[108:111]
	v_mfma_f32_16x16x32_bf16 v[104:107], v[128:131], v[172:175], v[104:107]
	v_mfma_f32_16x16x32_bf16 v[92:95], v[112:115], v[188:191], v[92:95]
	v_mfma_f32_16x16x32_bf16 v[88:91], v[128:131], v[188:191], v[88:91]
	v_mfma_f32_16x16x32_bf16 v[76:79], v[112:115], v[210:213], v[76:79]
	v_mfma_f32_16x16x32_bf16 v[72:75], v[128:131], v[210:213], v[72:75]
	v_mfma_f32_16x16x32_bf16 v[152:155], v[116:119], v[168:171], v[152:155]
	v_mfma_f32_16x16x32_bf16 v[148:151], v[132:135], v[168:171], v[148:151]
	v_mfma_f32_16x16x32_bf16 v[108:111], v[116:119], v[176:179], v[108:111]
	v_mfma_f32_16x16x32_bf16 v[104:107], v[132:135], v[176:179], v[104:107]
	v_mfma_f32_16x16x32_bf16 v[92:95], v[116:119], v[206:209], v[92:95]
	v_mfma_f32_16x16x32_bf16 v[88:91], v[132:135], v[206:209], v[88:91]
	v_mfma_f32_16x16x32_bf16 v[76:79], v[116:119], v[214:217], v[76:79]
	v_mfma_f32_16x16x32_bf16 v[72:75], v[132:135], v[214:217], v[72:75]
	s_setprio 0
	s_setprio 1
	v_mfma_f32_16x16x32_bf16 v[124:127], v[140:143], v[164:167], v[124:127]
	v_mfma_f32_16x16x32_bf16 v[120:123], v[156:159], v[164:167], v[120:123]
	v_mfma_f32_16x16x32_bf16 v[100:103], v[140:143], v[172:175], v[100:103]
	v_mfma_f32_16x16x32_bf16 v[96:99], v[156:159], v[172:175], v[96:99]
	v_mfma_f32_16x16x32_bf16 v[84:87], v[140:143], v[188:191], v[84:87]
	v_mfma_f32_16x16x32_bf16 v[80:83], v[156:159], v[188:191], v[80:83]
	v_mfma_f32_16x16x32_bf16 v[68:71], v[140:143], v[210:213], v[68:71]
	v_mfma_f32_16x16x32_bf16 v[64:67], v[156:159], v[210:213], v[64:67]
	v_mfma_f32_16x16x32_bf16 v[124:127], v[144:147], v[168:171], v[124:127]
	v_mfma_f32_16x16x32_bf16 v[120:123], v[160:163], v[168:171], v[120:123]
	v_mfma_f32_16x16x32_bf16 v[100:103], v[144:147], v[176:179], v[100:103]
	v_mfma_f32_16x16x32_bf16 v[96:99], v[160:163], v[176:179], v[96:99]
	v_mfma_f32_16x16x32_bf16 v[84:87], v[144:147], v[206:209], v[84:87]
	v_mfma_f32_16x16x32_bf16 v[80:83], v[160:163], v[206:209], v[80:83]
	v_mfma_f32_16x16x32_bf16 v[68:71], v[144:147], v[214:217], v[68:71]
	v_mfma_f32_16x16x32_bf16 v[64:67], v[160:163], v[214:217], v[64:67]
	s_setprio 0
	s_barrier
	s_add_u32 s46, s48, 0x40000
	s_addc_u32 s47, s49, 0
	s_add_i32 s6, s6, s25
	v_lshl_add_u64 v[218:219], s[46:47], 0, v[138:139]
	s_mov_b32 m0, s6
	ds_read_b128 v[164:167], v222 offset:49152
	ds_read_b128 v[168:171], v222 offset:50176
	ds_read_b128 v[172:175], v222 offset:51200
	ds_read_b128 v[176:179], v222 offset:52224
	ds_read_b128 v[188:191], v222 offset:53248
	ds_read_b128 v[206:209], v222 offset:54272
	ds_read_b128 v[210:213], v222 offset:55296
	ds_read_b128 v[214:217], v222 offset:56320
	global_load_lds_dwordx4 v[218:219], off
	s_add_i32 m0, s6, 0x2000
	v_lshl_add_u64 v[218:219], s[46:47], 0, v[136:137]
	s_add_u32 s46, s48, 0x42000
	s_addc_u32 s47, s49, 0
	s_add_i32 s6, s7, s25
	global_load_lds_dwordx4 v[218:219], off
	v_lshl_add_u64 v[218:219], s[46:47], 0, v[138:139]
	s_mov_b32 m0, s6
	v_lshl_add_u64 v[198:199], v[198:199], 0, s[36:37]
	global_load_lds_dwordx4 v[218:219], off
	v_lshl_add_u64 v[218:219], s[46:47], 0, v[136:137]
	s_add_i32 m0, s6, 0x2000
	s_nop 0
	global_load_lds_dwordx4 v[218:219], off
	s_mov_b32 m0, s58
	s_nop 0
	global_load_lds_dwordx4 v[198:199], off
	v_lshl_add_u64 v[198:199], v[200:201], 0, s[36:37]
	s_mov_b32 m0, s59
	s_nop 0
	global_load_lds_dwordx4 v[198:199], off
	s_add_u32 vcc_lo, vcc_lo, 0x2000
	s_addc_u32 vcc_hi, vcc_hi, 0
	s_mov_b32 m0, 0x22c00
	s_nop 0
	global_load_lds_dwordx4 v224, vcc
	s_waitcnt vmcnt(10)
	s_waitcnt lgkmcnt(0)
	s_barrier
; #define PG8_MMA(ai, bj, At, Bt) do { __builtin_amdgcn_s_setprio(1); _Pragma("unroll") for (int m = 0; m < 4; ++m) _Pragma("unroll") for (int n = 0; n < 2; ++n) _Pragma("unroll") for (int k = 0; k < 2; ++k) \
;         acc[ai][bj][m][n] = __builtin_amdgcn_mfma_f32_16x16x32_bf16(Bt[n][k], At[m][k], acc[ai][bj][m][n], 0, 0, 0); __builtin_amdgcn_s_setprio(0); } while (0)
; #define PG8_WAIT_V(n) asm volatile("s_waitcnt vmcnt(" #n ")" ::: "memory")
; #define PG8_WAIT_L(n) asm volatile("s_waitcnt lgkmcnt(" #n ")" ::: "memory")
; #define PG8_BAR __builtin_amdgcn_s_barrier()
; #define PG8_SCHED __builtin_amdgcn_sched_barrier(0)
; template <class Epi, bool ALIGN_EPI>
; __device__ __forceinline__ void gemm_phase(LAS unsigned char* lds, const Gemm g, int G, int cid, const Epi& E) {
;     ...
;             PG8_WAIT_V(8); PG8_WAIT_L(0); PG8_BAR; PG8_MMA(1, 0, At, B0); PG8_MMA(1, 1, At, B1); PG8_BAR; PG8_SCHED;
;         }
	s_setprio 1
	s_waitcnt lgkmcnt(0)
	v_mfma_f32_16x16x32_bf16 v[60:63], v[112:115], v[164:167], v[60:63]
	v_mfma_f32_16x16x32_bf16 v[56:59], v[128:131], v[164:167], v[56:59]
	v_mfma_f32_16x16x32_bf16 v[44:47], v[112:115], v[172:175], v[44:47]
	v_mfma_f32_16x16x32_bf16 v[40:43], v[128:131], v[172:175], v[40:43]
	v_mfma_f32_16x16x32_bf16 v[28:31], v[112:115], v[188:191], v[28:31]
	v_mfma_f32_16x16x32_bf16 v[24:27], v[128:131], v[188:191], v[24:27]
	v_mfma_f32_16x16x32_bf16 v[12:15], v[112:115], v[210:213], v[12:15]
	v_mfma_f32_16x16x32_bf16 v[8:11], v[128:131], v[210:213], v[8:11]
	v_mfma_f32_16x16x32_bf16 v[60:63], v[116:119], v[168:171], v[60:63]
	v_mfma_f32_16x16x32_bf16 v[56:59], v[132:135], v[168:171], v[56:59]
	v_mfma_f32_16x16x32_bf16 v[44:47], v[116:119], v[176:179], v[44:47]
	v_mfma_f32_16x16x32_bf16 v[40:43], v[132:135], v[176:179], v[40:43]
	v_mfma_f32_16x16x32_bf16 v[28:31], v[116:119], v[206:209], v[28:31]
	v_mfma_f32_16x16x32_bf16 v[24:27], v[132:135], v[206:209], v[24:27]
	v_mfma_f32_16x16x32_bf16 v[12:15], v[116:119], v[214:217], v[12:15]
	v_mfma_f32_16x16x32_bf16 v[8:11], v[132:135], v[214:217], v[8:11]
	s_setprio 0
	s_setprio 1
	v_mfma_f32_16x16x32_bf16 v[52:55], v[140:143], v[164:167], v[52:55]
	v_mfma_f32_16x16x32_bf16 v[48:51], v[156:159], v[164:167], v[48:51]
	v_mfma_f32_16x16x32_bf16 v[36:39], v[140:143], v[172:175], v[36:39]
	v_mfma_f32_16x16x32_bf16 v[32:35], v[156:159], v[172:175], v[32:35]
	v_mfma_f32_16x16x32_bf16 v[20:23], v[140:143], v[188:191], v[20:23]
	v_mfma_f32_16x16x32_bf16 v[16:19], v[156:159], v[188:191], v[16:19]
	v_mfma_f32_16x16x32_bf16 v[4:7], v[140:143], v[210:213], v[4:7]
	v_mfma_f32_16x16x32_bf16 v[0:3], v[156:159], v[210:213], v[0:3]
	v_mfma_f32_16x16x32_bf16 v[52:55], v[144:147], v[168:171], v[52:55]
	v_mfma_f32_16x16x32_bf16 v[48:51], v[160:163], v[168:171], v[48:51]
	v_mfma_f32_16x16x32_bf16 v[36:39], v[144:147], v[176:179], v[36:39]
	v_mfma_f32_16x16x32_bf16 v[32:35], v[160:163], v[176:179], v[32:35]
	v_mfma_f32_16x16x32_bf16 v[20:23], v[144:147], v[206:209], v[20:23]
	v_mfma_f32_16x16x32_bf16 v[16:19], v[160:163], v[206:209], v[16:19]
	v_mfma_f32_16x16x32_bf16 v[4:7], v[144:147], v[214:217], v[4:7]
	v_mfma_f32_16x16x32_bf16 v[0:3], v[160:163], v[214:217], v[0:3]
	s_setprio 0
	s_barrier
	s_add_i32 s77, s77, 2
	s_add_u32 s75, s75, 0x80000
	s_addc_u32 s76, s76, 0
	s_cmp_gt_u32 s77, 29
	s_mov_b64 s[46:47], s[42:43]
	s_cbranch_scc0 .LBB0_727
;     __device__ __forceinline__ void operator()(const f32x4 (&acc)[2][2][4][2], const Unit& u, int wr, int wc, int fr, int fq, const LAS float*) const {
;         const int row0 = u.pm * BM + wr * 64 + fr, col0 = u.pn * BM + wc * 32 + 8 * fq;
;         f32x4 bv[2][2], sv[2][2];
; #pragma unroll
;         for (int bj = 0; bj < 2; ++bj)
; #pragma unroll
;             for (int n = 0; n < 2; ++n) { bv[bj][n] = HB ? *(const f32x4*)(bias + col0 + bj * HALF + 4 * n) : (f32x4){0.f, 0.f, 0.f, 0.f};
;                                            sv[bj][n] = HB ? *(const f32x4*)(scale + col0 + bj * HALF + 4 * n) : (f32x4){1.f, 1.f, 1.f, 1.f}; }
;         constexpr int NB = HB ? 4 : 2, MB = 4 / (NB / 2);
; #pragma unroll
;         for (int am = 0; am < NB; ++am) { const int ai = am / (NB / 2), m0 = (am % (NB / 2)) * MB;
;             f32x4 xo[4][2][2];
; #pragma unroll
;             for (int m = m0; m < m0 + MB; ++m) { const float* xr = Xs + (size_t)(row0 + ai * HALF + m * 16) * DM + col0;
; #pragma unroll
;                 for (int bj = 0; bj < 2; ++bj) { xo[m][bj][0] = *(const f32x4*)(xr + bj * HALF); xo[m][bj][1] = *(const f32x4*)(xr + bj * HALF + 4); } }
; #pragma unroll
;             for (int m = m0; m < m0 + MB; ++m) { const int row = row0 + ai * HALF + m * 16; float ss = 0.f;
;                 float* xr = X + (size_t)row * DM + col0; bf16_t* xb = XB + (size_t)row * ALD + col0;
; #pragma unroll
;                 for (int bj = 0; bj < 2; ++bj) { f32x4 x0 = xo[m][bj][0], x1 = xo[m][bj][1];
;                     if (HB) { x0 += (acc[ai][bj][m][0] + bv[bj][0]) * sv[bj][0]; x1 += (acc[ai][bj][m][1] + bv[bj][1]) * sv[bj][1]; } else { x0 += acc[ai][bj][m][0]; x1 += acc[ai][bj][m][1]; }
;                     *(f32x4*)(xr + bj * HALF) = x0; *(f32x4*)(xr + bj * HALF + 4) = x1;
;                     ss += (x0[0] * x0[0] + x0[1] * x0[1]) + (x0[2] * x0[2] + x0[3] * x0[3]) + (x1[0] * x1[0] + x1[1] * x1[1]) + (x1[2] * x1[2] + x1[3] * x1[3]);
;                     u32x4 w; w.x = cvt_pk_bf16(x0[0], x0[1]); w.y = cvt_pk_bf16(x0[2], x0[3]); w.z = cvt_pk_bf16(x1[0], x1[1]); w.w = cvt_pk_bf16(x1[2], x1[3]);
;                     if (feeds) *(u32x4*)(xb + bj * HALF) = w; }
;                 ss += __shfl_xor(ss, 16); ss += __shfl_xor(ss, 32);
;                 if (fq == 0 && feeds) part[(size_t)row * NPART + u.pn * 4 + wc] = ss; }
	v_lshl_or_b32 v188, s12, 8, v221
	v_lshl_add_u32 v190, s13, 8, v197
	v_ashrrev_i32_e32 v189, 31, v188
	v_lshlrev_b64 v[198:199], 2, v[188:189]
	v_ashrrev_i32_e32 v191, 31, v190
	v_lshl_add_u64 v[206:207], s[22:23], 0, v[198:199]
	v_lshlrev_b64 v[200:201], 13, v[190:191]
	v_lshl_add_u64 v[112:113], v[206:207], 0, v[200:201]
	global_load_dwordx4 v[224:227], v[112:113], off offset:16
	global_load_dwordx4 v[228:231], v[112:113], off
	global_load_dwordx4 v[232:235], v[112:113], off offset:528
	global_load_dwordx4 v[244:247], v[112:113], off offset:512
	v_or_b32_e32 v214, 16, v190
	v_ashrrev_i32_e32 v215, 31, v214
	v_or_b32_e32 v210, 32, v190
	v_or_b32_e32 v208, 48, v190
	v_lshlrev_b64 v[218:219], 13, v[214:215]
	v_ashrrev_i32_e32 v211, 31, v210
	v_ashrrev_i32_e32 v209, 31, v208
	v_lshl_add_u64 v[112:113], v[206:207], 0, v[218:219]
	v_lshlrev_b64 v[216:217], 13, v[210:211]
	v_lshlrev_b64 v[212:213], 13, v[208:209]
	global_load_dwordx4 v[172:175], v[112:113], off offset:16
	global_load_dwordx4 v[176:179], v[112:113], off
	global_load_dwordx4 v[164:167], v[112:113], off offset:528
	global_load_dwordx4 v[168:171], v[112:113], off offset:512
	v_lshl_add_u64 v[112:113], v[206:207], 0, v[216:217]
	v_lshl_add_u64 v[116:117], v[206:207], 0, v[212:213]
	global_load_dwordx4 v[156:159], v[112:113], off offset:16
	global_load_dwordx4 v[160:163], v[112:113], off
	global_load_dwordx4 v[128:131], v[112:113], off offset:528
	global_load_dwordx4 v[144:147], v[112:113], off offset:512
	global_load_dwordx4 v[132:135], v[116:117], off offset:16
	global_load_dwordx4 v[140:143], v[116:117], off
	s_nop 0
	global_load_dwordx4 v[112:115], v[116:117], off offset:528
	s_nop 0
	global_load_dwordx4 v[116:119], v[116:117], off offset:512
	v_lshl_add_u64 v[200:201], s[82:83], 0, v[200:201]
	v_lshl_add_u64 v[198:199], v[200:201], 0, v[198:199]
	v_mov_b64_e32 v[200:201], s[4:5]
	s_lshl_b32 s42, s12, 2
	v_mad_i64_i32 v[200:201], s[12:13], v190, s66, v[200:201]
	v_lshl_add_u64 v[200:201], v[188:189], 1, v[200:201]
	s_ashr_i32 s43, s42, 31
	s_waitcnt vmcnt(12)
	v_pk_add_f32 v[148:149], v[148:149], v[224:225]
	v_pk_add_f32 v[154:155], v[154:155], v[230:231]
	v_pk_add_f32 v[152:153], v[152:153], v[228:229]
	v_mul_f32_e32 v224, v155, v155
	v_mul_f32_e32 v223, v153, v153
	v_fmac_f32_e32 v223, v152, v152
	v_fmac_f32_e32 v224, v154, v154
	v_add_f32_e32 v223, v223, v224
	v_mul_f32_e32 v224, v149, v149
	v_pk_add_f32 v[126:127], v[126:127], v[246:247]
	v_pk_add_f32 v[124:125], v[124:125], v[244:245]
	v_pk_add_f32 v[150:151], v[150:151], v[226:227]
	global_store_dwordx4 v[198:199], v[152:155], off
	global_store_dwordx4 v[198:199], v[148:151], off offset:16
	v_fmac_f32_e32 v224, v148, v148
	v_cvt_pk_bf16_f32 v152, v152, v153
	v_cvt_pk_bf16_f32 v153, v154, v155
	v_cvt_pk_bf16_f32 v154, v148, v149
	v_pk_add_f32 v[120:121], v[120:121], v[232:233]
	v_mul_f32_e32 v148, v125, v125
	v_mul_f32_e32 v149, v127, v127
	v_fmac_f32_e32 v148, v124, v124
	v_fmac_f32_e32 v149, v126, v126
	v_add_f32_e32 v148, v148, v149
	v_mul_f32_e32 v149, v121, v121
	v_cvt_pk_bf16_f32 v155, v150, v151
	global_store_dwordx4 v[200:201], v[152:155], off
	v_pk_add_f32 v[122:123], v[122:123], v[234:235]
	global_store_dwordx4 v[198:199], v[124:127], off offset:512
	global_store_dwordx4 v[198:199], v[120:123], off offset:528
	v_fmac_f32_e32 v149, v120, v120
	v_cvt_pk_bf16_f32 v124, v124, v125
	v_cvt_pk_bf16_f32 v125, v126, v127
	v_cvt_pk_bf16_f32 v126, v120, v121
	v_add_f32_e32 v223, v223, v224
	v_and_b32_e32 v121, 64, v239
	v_mul_f32_e32 v224, v151, v151
	v_add_f32_e32 v148, v148, v149
	v_mul_f32_e32 v149, v123, v123
	v_xor_b32_e32 v120, 16, v239
	v_add_u32_e32 v121, 64, v121
	v_fmac_f32_e32 v224, v150, v150
	v_fmac_f32_e32 v149, v122, v122
	v_cmp_lt_i32_e32 vcc, v120, v121
	v_add_f32_e32 v223, v224, v223
	v_add_f32_e32 v148, v149, v148
	v_cndmask_b32_e32 v120, v239, v120, vcc
	v_add_f32_e32 v148, v223, v148
	v_cvt_pk_bf16_f32 v127, v122, v123
	global_store_dwordx4 v[200:201], v[124:127], off offset:256
	v_xor_b32_e32 v122, 32, v239
	v_cmp_lt_i32_e32 vcc, v122, v121
	v_lshlrev_b32_e32 v126, 2, v120
	ds_bpermute_b32 v120, v126, v148
	v_cndmask_b32_e32 v121, v239, v122, vcc
	v_lshlrev_b32_e32 v127, 2, v121
	s_waitcnt lgkmcnt(0)
	v_add_f32_e32 v120, v148, v120
	ds_bpermute_b32 v121, v127, v120
	s_and_saveexec_b64 s[46:47], s[38:39]
	s_cbranch_execz .LBB0_730
	v_lshlrev_b64 v[122:123], 7, v[190:191]
	v_lshl_add_u64 v[122:123], s[94:95], 0, v[122:123]
	v_lshl_add_u64 v[122:123], s[42:43], 2, v[122:123]
	s_lshl_b32 s30, s57, 2
	v_lshl_add_u64 v[122:123], v[122:123], 0, s[30:31]
	s_waitcnt lgkmcnt(0)
	v_add_f32_e32 v120, v120, v121
	global_store_dword v[122:123], v120, off

; #define PG8_STAGE(bufoff, gbase, voff) do { _Pragma("unroll") for (int _i = 0; _i < 2; ++_i) \
;         __builtin_amdgcn_global_load_lds((const unsigned*)((const char*)(gbase) + (voff)[_i]), (LAS unsigned*)(lds + (bufoff) + ldsw + _i * 8192), 16, 0, 0); } while (0)
; #define PG8_LDA(dst, b, h) do { _Pragma("unroll") for (int m = 0; m < 4; ++m) _Pragma("unroll") for (int k = 0; k < 2; ++k) dst[m][k] = *(const LAS bf16x8*)(lds + PG8_SA(b, h) + aoff + m * 2048 + k * 1024); } while (0)
; #define PG8_LDB(dst, b, h) do { _Pragma("unroll") for (int n = 0; n < 2; ++n) _Pragma("unroll") for (int k = 0; k < 2; ++k) dst[n][k] = *(const LAS bf16x8*)(lds + PG8_SB(b, h) + boff + n * 2048 + k * 1024); } while (0)
; #define PG8_MMA(ai, bj, At, Bt) do { __builtin_amdgcn_s_setprio(1); _Pragma("unroll") for (int m = 0; m < 4; ++m) _Pragma("unroll") for (int n = 0; n < 2; ++n) _Pragma("unroll") for (int k = 0; k < 2; ++k) \
;         acc[ai][bj][m][n] = __builtin_amdgcn_mfma_f32_16x16x32_bf16(Bt[n][k], At[m][k], acc[ai][bj][m][n], 0, 0, 0); __builtin_amdgcn_s_setprio(0); } while (0)
; #define PG8_WAIT_V(n) asm volatile("s_waitcnt vmcnt(" #n ")" ::: "memory")
; #define PG8_WAIT_L(n) asm volatile("s_waitcnt lgkmcnt(" #n ")" ::: "memory")
; #define PG8_BAR __builtin_amdgcn_s_barrier()
; #define PG8_SCHED __builtin_amdgcn_sched_barrier(0)
; template <class Epi, bool ALIGN_EPI>
; __device__ __forceinline__ void gemm_phase(LAS unsigned char* lds, const Gemm g, int G, int cid, const Epi& E) {
;     ...
;         for (int t = 0; t < nt; t += 2) {
;             const bool last = (t == nt - 2);
;             const char* a1 = cA + (size_t)(t + 1) * kA;
;             const char* a2 = last ? nA : cA + (size_t)(t + 2) * kA; const char* b2 = last ? nB : cB + (size_t)(t + 2) * kB;
;             const char* a3 = a2 + kA; const char* b3 = b2 + kB;
;             PG8_LDB(B0, 0, 0); PG8_LDB(B1, 0, 1); PG8_SCHED; PG8_LDA(At, 0, 0); PG8_STAGE(PG8_SA(1, 1), a1 + hA, voffA);
;             PG8_WAIT_V(8); PG8_WAIT_L(0); PG8_BAR; PG8_MMA(0, 0, At, B0); PG8_MMA(0, 1, At, B1); PG8_BAR; PG8_SCHED;
;             PG8_LDA(At, 0, 1); PG8_STAGE(PG8_SB(0, 0), b2, voffB); PG8_STAGE(PG8_SB(0, 1), b2 + hB, voffB); PG8_STAGE(PG8_SA(0, 0), a2, voffA);
;             PG8_WAIT_V(8); PG8_WAIT_L(0); PG8_BAR; PG8_MMA(1, 0, At, B0); PG8_MMA(1, 1, At, B1); PG8_BAR; PG8_SCHED;
.LBB0_927:
	s_add_u32 s40, s48, 0x100
	s_addc_u32 s41, s49, 0
	s_add_i32 s6, 0, 0x10000
	s_cmpk_eq_i32 s79, 0x54
	s_cselect_b32 s53, s45, s41
	s_cselect_b32 s52, s44, s40
	s_cselect_b32 s51, s30, s78
	s_cselect_b32 s50, s76, s77
	s_add_i32 s86, 0, 0x14000
	v_add_u32_e32 v144, s6, v243
	v_add_u32_e32 v160, s86, v243
	ds_read_b128 v[128:131], v144
	ds_read_b128 v[132:135], v144 offset:1024
	ds_read_b128 v[140:143], v144 offset:2048
	ds_read_b128 v[144:147], v144 offset:3072
	ds_read_b128 v[148:151], v160
	ds_read_b128 v[152:155], v160 offset:1024
	ds_read_b128 v[156:159], v160 offset:2048
	ds_read_b128 v[160:163], v160 offset:3072
	v_lshl_add_u64 v[198:199], s[48:49], 0, v[210:211]
	s_add_i32 m0, s12, 0xc000
	ds_read_b128 v[164:167], v245
	ds_read_b128 v[168:171], v245 offset:1024
	ds_read_b128 v[172:175], v245 offset:2048
	ds_read_b128 v[176:179], v245 offset:3072
	ds_read_b128 v[180:183], v245 offset:4096
	ds_read_b128 v[184:187], v245 offset:5120
	ds_read_b128 v[188:191], v245 offset:6144
	ds_read_b128 v[214:217], v245 offset:7168
	global_load_lds_dwordx4 v[198:199], off
	v_lshl_add_u64 v[198:199], s[48:49], 0, v[212:213]
	s_add_i32 m0, s12, 0xe000
	s_nop 0
	global_load_lds_dwordx4 v[198:199], off
	s_waitcnt vmcnt(8)
	s_waitcnt lgkmcnt(0)
	s_barrier
	s_setprio 1
	s_waitcnt lgkmcnt(0)
	v_mfma_f32_16x16x32_bf16 v[124:127], v[128:131], v[164:167], v[124:127]
	v_mfma_f32_16x16x32_bf16 v[120:123], v[140:143], v[164:167], v[120:123]
	v_mfma_f32_16x16x32_bf16 v[108:111], v[128:131], v[172:175], v[108:111]
	v_mfma_f32_16x16x32_bf16 v[104:107], v[140:143], v[172:175], v[104:107]
	v_mfma_f32_16x16x32_bf16 v[92:95], v[128:131], v[180:183], v[92:95]
	v_mfma_f32_16x16x32_bf16 v[88:91], v[140:143], v[180:183], v[88:91]
	v_mfma_f32_16x16x32_bf16 v[76:79], v[128:131], v[188:191], v[76:79]
	v_mfma_f32_16x16x32_bf16 v[72:75], v[140:143], v[188:191], v[72:75]
	v_mfma_f32_16x16x32_bf16 v[124:127], v[132:135], v[168:171], v[124:127]
	v_mfma_f32_16x16x32_bf16 v[120:123], v[144:147], v[168:171], v[120:123]
	v_mfma_f32_16x16x32_bf16 v[108:111], v[132:135], v[176:179], v[108:111]
	v_mfma_f32_16x16x32_bf16 v[104:107], v[144:147], v[176:179], v[104:107]
	v_mfma_f32_16x16x32_bf16 v[92:95], v[132:135], v[184:187], v[92:95]
	v_mfma_f32_16x16x32_bf16 v[88:91], v[144:147], v[184:187], v[88:91]
	v_mfma_f32_16x16x32_bf16 v[76:79], v[132:135], v[214:217], v[76:79]
	v_mfma_f32_16x16x32_bf16 v[72:75], v[144:147], v[214:217], v[72:75]
	s_setprio 0
	s_setprio 1
	v_mfma_f32_16x16x32_bf16 v[116:119], v[148:151], v[164:167], v[116:119]
	v_mfma_f32_16x16x32_bf16 v[112:115], v[156:159], v[164:167], v[112:115]
	v_mfma_f32_16x16x32_bf16 v[100:103], v[148:151], v[172:175], v[100:103]
	v_mfma_f32_16x16x32_bf16 v[96:99], v[156:159], v[172:175], v[96:99]
	v_mfma_f32_16x16x32_bf16 v[84:87], v[148:151], v[180:183], v[84:87]
	v_mfma_f32_16x16x32_bf16 v[80:83], v[156:159], v[180:183], v[80:83]
	v_mfma_f32_16x16x32_bf16 v[68:71], v[148:151], v[188:191], v[68:71]
	v_mfma_f32_16x16x32_bf16 v[64:67], v[156:159], v[188:191], v[64:67]
	v_mfma_f32_16x16x32_bf16 v[116:119], v[152:155], v[168:171], v[116:119]
	v_mfma_f32_16x16x32_bf16 v[112:115], v[160:163], v[168:171], v[112:115]
	v_mfma_f32_16x16x32_bf16 v[100:103], v[152:155], v[176:179], v[100:103]
	v_mfma_f32_16x16x32_bf16 v[96:99], v[160:163], v[176:179], v[96:99]
	v_mfma_f32_16x16x32_bf16 v[84:87], v[152:155], v[184:187], v[84:87]
	v_mfma_f32_16x16x32_bf16 v[80:83], v[160:163], v[184:187], v[80:83]
	v_mfma_f32_16x16x32_bf16 v[68:71], v[152:155], v[214:217], v[68:71]
	v_mfma_f32_16x16x32_bf16 v[64:67], v[160:163], v[214:217], v[64:67]
	s_setprio 0
	s_barrier
	s_add_i32 s6, s6, s25
	v_lshl_add_u64 v[198:199], s[50:51], 0, v[138:139]
	s_mov_b32 m0, s6
	ds_read_b128 v[164:167], v245 offset:16384
	ds_read_b128 v[168:171], v245 offset:17408
	ds_read_b128 v[172:175], v245 offset:18432
	ds_read_b128 v[176:179], v245 offset:19456
	ds_read_b128 v[180:183], v245 offset:20480
	ds_read_b128 v[184:187], v245 offset:21504
	ds_read_b128 v[188:191], v245 offset:22528
	ds_read_b128 v[214:217], v245 offset:23552
	global_load_lds_dwordx4 v[198:199], off
	s_add_i32 m0, s6, 0x2000
	s_add_u32 s6, s50, 0x2000
	v_lshl_add_u64 v[198:199], s[50:51], 0, v[136:137]
	s_addc_u32 s7, s51, 0
	s_add_i32 s48, s86, s25
	global_load_lds_dwordx4 v[198:199], off
	v_lshl_add_u64 v[198:199], s[6:7], 0, v[138:139]
	s_mov_b32 m0, s48
	v_lshl_add_u64 v[200:201], s[52:53], 0, v[206:207]
	global_load_lds_dwordx4 v[198:199], off
	v_lshl_add_u64 v[198:199], s[6:7], 0, v[136:137]
	s_add_i32 m0, s48, 0x2000
	s_nop 0
	global_load_lds_dwordx4 v[198:199], off
	v_lshl_add_u64 v[198:199], s[52:53], 0, v[208:209]
	s_mov_b32 m0, s12
	s_nop 0
	global_load_lds_dwordx4 v[198:199], off
	s_mov_b32 m0, s13
	s_nop 0
	global_load_lds_dwordx4 v[200:201], off
	s_add_i32 vcc_lo, s79, 2
	s_lshl_b32 vcc_lo, vcc_lo, 15
	s_and_b32 vcc_lo, vcc_lo, 0x1f0000
	s_lshl_b32 vcc_hi, s75, 21
	s_add_i32 vcc_lo, vcc_lo, vcc_hi
	s_lshl_b32 vcc_hi, s25, 3
	s_add_i32 vcc_lo, vcc_lo, vcc_hi
	s_lshl_b32 vcc_hi, s74, 10
	s_add_i32 vcc_lo, vcc_lo, vcc_hi
	s_add_u32 vcc_lo, s82, vcc_lo
	s_addc_u32 vcc_hi, s83, 0
	s_mov_b32 m0, 0x22c00
	s_nop 0
	global_load_lds_dwordx4 v226, vcc
	s_waitcnt vmcnt(9)
	s_waitcnt lgkmcnt(0)
	s_barrier
; #define PG8_STAGE(bufoff, gbase, voff) do { _Pragma("unroll") for (int _i = 0; _i < 2; ++_i) \
;         __builtin_amdgcn_global_load_lds((const unsigned*)((const char*)(gbase) + (voff)[_i]), (LAS unsigned*)(lds + (bufoff) + ldsw + _i * 8192), 16, 0, 0); } while (0)
; #define PG8_LDA(dst, b, h) do { _Pragma("unroll") for (int m = 0; m < 4; ++m) _Pragma("unroll") for (int k = 0; k < 2; ++k) dst[m][k] = *(const LAS bf16x8*)(lds + PG8_SA(b, h) + aoff + m * 2048 + k * 1024); } while (0)
; #define PG8_LDB(dst, b, h) do { _Pragma("unroll") for (int n = 0; n < 2; ++n) _Pragma("unroll") for (int k = 0; k < 2; ++k) dst[n][k] = *(const LAS bf16x8*)(lds + PG8_SB(b, h) + boff + n * 2048 + k * 1024); } while (0)
; #define PG8_MMA(ai, bj, At, Bt) do { __builtin_amdgcn_s_setprio(1); _Pragma("unroll") for (int m = 0; m < 4; ++m) _Pragma("unroll") for (int n = 0; n < 2; ++n) _Pragma("unroll") for (int k = 0; k < 2; ++k) \
;         acc[ai][bj][m][n] = __builtin_amdgcn_mfma_f32_16x16x32_bf16(Bt[n][k], At[m][k], acc[ai][bj][m][n], 0, 0, 0); __builtin_amdgcn_s_setprio(0); } while (0)
; #define PG8_WAIT_V(n) asm volatile("s_waitcnt vmcnt(" #n ")" ::: "memory")
; #define PG8_WAIT_L(n) asm volatile("s_waitcnt lgkmcnt(" #n ")" ::: "memory")
; #define PG8_BAR __builtin_amdgcn_s_barrier()
; #define PG8_SCHED __builtin_amdgcn_sched_barrier(0)
; template <class Epi, bool ALIGN_EPI>
; __device__ __forceinline__ void gemm_phase(LAS unsigned char* lds, const Gemm g, int G, int cid, const Epi& E) {
;     ...
;             PG8_WAIT_V(8); PG8_WAIT_L(0); PG8_BAR; PG8_MMA(1, 0, At, B0); PG8_MMA(1, 1, At, B1); PG8_BAR; PG8_SCHED;
;             PG8_LDB(B0, 1, 0); PG8_LDB(B1, 1, 1); PG8_SCHED; PG8_LDA(At, 1, 0); PG8_STAGE(PG8_SA(0, 1), a2 + hA, voffA);
;             PG8_WAIT_V(8); PG8_WAIT_L(0); PG8_BAR; PG8_MMA(0, 0, At, B0); PG8_MMA(0, 1, At, B1); PG8_BAR; PG8_SCHED;
	s_setprio 1
	s_waitcnt lgkmcnt(0)
	v_mfma_f32_16x16x32_bf16 v[60:63], v[128:131], v[164:167], v[60:63]
	v_mfma_f32_16x16x32_bf16 v[56:59], v[140:143], v[164:167], v[56:59]
	v_mfma_f32_16x16x32_bf16 v[44:47], v[128:131], v[172:175], v[44:47]
	v_mfma_f32_16x16x32_bf16 v[40:43], v[140:143], v[172:175], v[40:43]
	v_mfma_f32_16x16x32_bf16 v[28:31], v[128:131], v[180:183], v[28:31]
	v_mfma_f32_16x16x32_bf16 v[24:27], v[140:143], v[180:183], v[24:27]
	v_mfma_f32_16x16x32_bf16 v[12:15], v[128:131], v[188:191], v[12:15]
	v_mfma_f32_16x16x32_bf16 v[8:11], v[140:143], v[188:191], v[8:11]
	v_mfma_f32_16x16x32_bf16 v[60:63], v[132:135], v[168:171], v[60:63]
	v_mfma_f32_16x16x32_bf16 v[56:59], v[144:147], v[168:171], v[56:59]
	v_mfma_f32_16x16x32_bf16 v[44:47], v[132:135], v[176:179], v[44:47]
	v_mfma_f32_16x16x32_bf16 v[40:43], v[144:147], v[176:179], v[40:43]
	v_mfma_f32_16x16x32_bf16 v[28:31], v[132:135], v[184:187], v[28:31]
	v_mfma_f32_16x16x32_bf16 v[24:27], v[144:147], v[184:187], v[24:27]
	v_mfma_f32_16x16x32_bf16 v[12:15], v[132:135], v[214:217], v[12:15]
	v_mfma_f32_16x16x32_bf16 v[8:11], v[144:147], v[214:217], v[8:11]
	s_setprio 0
	s_setprio 1
	v_mfma_f32_16x16x32_bf16 v[52:55], v[148:151], v[164:167], v[52:55]
	v_mfma_f32_16x16x32_bf16 v[48:51], v[156:159], v[164:167], v[48:51]
	v_mfma_f32_16x16x32_bf16 v[36:39], v[148:151], v[172:175], v[36:39]
	v_mfma_f32_16x16x32_bf16 v[32:35], v[156:159], v[172:175], v[32:35]
	v_mfma_f32_16x16x32_bf16 v[20:23], v[148:151], v[180:183], v[20:23]
	v_mfma_f32_16x16x32_bf16 v[16:19], v[156:159], v[180:183], v[16:19]
	v_mfma_f32_16x16x32_bf16 v[4:7], v[148:151], v[188:191], v[4:7]
	v_mfma_f32_16x16x32_bf16 v[0:3], v[156:159], v[188:191], v[0:3]
	v_mfma_f32_16x16x32_bf16 v[52:55], v[152:155], v[168:171], v[52:55]
	v_mfma_f32_16x16x32_bf16 v[48:51], v[160:163], v[168:171], v[48:51]
	v_mfma_f32_16x16x32_bf16 v[36:39], v[152:155], v[176:179], v[36:39]
	v_mfma_f32_16x16x32_bf16 v[32:35], v[160:163], v[176:179], v[32:35]
	v_mfma_f32_16x16x32_bf16 v[20:23], v[152:155], v[184:187], v[20:23]
	v_mfma_f32_16x16x32_bf16 v[16:19], v[160:163], v[184:187], v[16:19]
	v_mfma_f32_16x16x32_bf16 v[4:7], v[152:155], v[214:217], v[4:7]
	v_mfma_f32_16x16x32_bf16 v[0:3], v[160:163], v[214:217], v[0:3]
	s_setprio 0
	s_barrier
	s_add_i32 s48, 0, 0x18000
	s_add_i32 s49, 0, 0x1c000
	v_add_u32_e32 v144, s48, v243
	v_add_u32_e32 v160, s49, v243
	ds_read_b128 v[128:131], v144
	ds_read_b128 v[132:135], v144 offset:1024
	ds_read_b128 v[140:143], v144 offset:2048
	ds_read_b128 v[144:147], v144 offset:3072
	ds_read_b128 v[148:151], v160
	ds_read_b128 v[152:155], v160 offset:1024
	ds_read_b128 v[156:159], v160 offset:2048
	ds_read_b128 v[160:163], v160 offset:3072
	s_add_u32 s6, s52, 0x160000
	s_addc_u32 s7, s53, 0
	s_mov_b32 m0, s54
	v_lshl_add_u64 v[218:219], s[6:7], 0, v[208:209]
	ds_read_b128 v[164:167], v245 offset:32768
	ds_read_b128 v[168:171], v245 offset:33792
	ds_read_b128 v[172:175], v245 offset:34816
	ds_read_b128 v[176:179], v245 offset:35840
	ds_read_b128 v[180:183], v245 offset:36864
	ds_read_b128 v[184:187], v245 offset:37888
	ds_read_b128 v[188:191], v245 offset:38912
	ds_read_b128 v[214:217], v245 offset:39936
	global_load_lds_dwordx4 v[218:219], off
	v_lshl_add_u64 v[218:219], s[6:7], 0, v[206:207]
	s_mov_b32 m0, s55
	s_nop 0
	global_load_lds_dwordx4 v[218:219], off
	s_waitcnt vmcnt(9)
	s_waitcnt lgkmcnt(0)
	s_barrier
	s_setprio 1
	s_waitcnt lgkmcnt(0)
	v_mfma_f32_16x16x32_bf16 v[124:127], v[128:131], v[164:167], v[124:127]
	v_mfma_f32_16x16x32_bf16 v[120:123], v[140:143], v[164:167], v[120:123]
	v_mfma_f32_16x16x32_bf16 v[108:111], v[128:131], v[172:175], v[108:111]
	v_mfma_f32_16x16x32_bf16 v[104:107], v[140:143], v[172:175], v[104:107]
	v_mfma_f32_16x16x32_bf16 v[92:95], v[128:131], v[180:183], v[92:95]
	v_mfma_f32_16x16x32_bf16 v[88:91], v[140:143], v[180:183], v[88:91]
	v_mfma_f32_16x16x32_bf16 v[76:79], v[128:131], v[188:191], v[76:79]
	v_mfma_f32_16x16x32_bf16 v[72:75], v[140:143], v[188:191], v[72:75]
	v_mfma_f32_16x16x32_bf16 v[124:127], v[132:135], v[168:171], v[124:127]
	v_mfma_f32_16x16x32_bf16 v[120:123], v[144:147], v[168:171], v[120:123]
	v_mfma_f32_16x16x32_bf16 v[108:111], v[132:135], v[176:179], v[108:111]
	v_mfma_f32_16x16x32_bf16 v[104:107], v[144:147], v[176:179], v[104:107]
	v_mfma_f32_16x16x32_bf16 v[92:95], v[132:135], v[184:187], v[92:95]
	v_mfma_f32_16x16x32_bf16 v[88:91], v[144:147], v[184:187], v[88:91]
	v_mfma_f32_16x16x32_bf16 v[76:79], v[132:135], v[214:217], v[76:79]
	v_mfma_f32_16x16x32_bf16 v[72:75], v[144:147], v[214:217], v[72:75]
	s_setprio 0
	s_setprio 1
	v_mfma_f32_16x16x32_bf16 v[116:119], v[148:151], v[164:167], v[116:119]
	v_mfma_f32_16x16x32_bf16 v[112:115], v[156:159], v[164:167], v[112:115]
	v_mfma_f32_16x16x32_bf16 v[100:103], v[148:151], v[172:175], v[100:103]
	v_mfma_f32_16x16x32_bf16 v[96:99], v[156:159], v[172:175], v[96:99]
	v_mfma_f32_16x16x32_bf16 v[84:87], v[148:151], v[180:183], v[84:87]
	v_mfma_f32_16x16x32_bf16 v[80:83], v[156:159], v[180:183], v[80:83]
	v_mfma_f32_16x16x32_bf16 v[68:71], v[148:151], v[188:191], v[68:71]
	v_mfma_f32_16x16x32_bf16 v[64:67], v[156:159], v[188:191], v[64:67]
	v_mfma_f32_16x16x32_bf16 v[116:119], v[152:155], v[168:171], v[116:119]
	v_mfma_f32_16x16x32_bf16 v[112:115], v[160:163], v[168:171], v[112:115]
	v_mfma_f32_16x16x32_bf16 v[100:103], v[152:155], v[176:179], v[100:103]
	v_mfma_f32_16x16x32_bf16 v[96:99], v[160:163], v[176:179], v[96:99]
	v_mfma_f32_16x16x32_bf16 v[84:87], v[152:155], v[184:187], v[84:87]
	v_mfma_f32_16x16x32_bf16 v[80:83], v[160:163], v[184:187], v[80:83]
	v_mfma_f32_16x16x32_bf16 v[68:71], v[152:155], v[214:217], v[68:71]
	v_mfma_f32_16x16x32_bf16 v[64:67], v[160:163], v[214:217], v[64:67]
	s_setprio 0
	s_barrier
; #define PG8_BAR __builtin_amdgcn_s_barrier()
; template <class Epi, bool ALIGN_EPI>
; __device__ __forceinline__ void gemm_phase(LAS unsigned char* lds, const Gemm g, int G, int cid, const Epi& E) {
;     ...
;             PG8_WAIT_V(8); PG8_WAIT_L(0); PG8_BAR; PG8_MMA(0, 0, At, B0); PG8_MMA(0, 1, At, B1); PG8_BAR; PG8_SCHED;
;             PG8_LDA(At, 1, 1); PG8_STAGE(PG8_SB(1, 0), b3, voffB); PG8_STAGE(PG8_SB(1, 1), b3 + hB, voffB); PG8_STAGE(PG8_SA(1, 0), a3, voffA);
;             PG8_WAIT_V(8); PG8_WAIT_L(0); PG8_BAR; PG8_MMA(1, 0, At, B0); PG8_MMA(1, 1, At, B1); PG8_BAR; PG8_SCHED;
;         }
;     __device__ __forceinline__ void operator()(const f32x4 (&acc)[2][2][4][2], const Unit& u, int wr, int wc, int fr, int fq, const LAS float*) const {
;         const int row0 = u.pm * BM + wr * 64 + fr, col0 = u.pn * BM + wc * 32 + 8 * fq;
;         f32x4 bv[2][2], sv[2][2];
; #pragma unroll
;         for (int bj = 0; bj < 2; ++bj)
; #pragma unroll
;             for (int n = 0; n < 2; ++n) { bv[bj][n] = HB ? *(const f32x4*)(bias + col0 + bj * HALF + 4 * n) : (f32x4){0.f, 0.f, 0.f, 0.f};
;                                            sv[bj][n] = HB ? *(const f32x4*)(scale + col0 + bj * HALF + 4 * n) : (f32x4){1.f, 1.f, 1.f, 1.f}; }
;         constexpr int NB = HB ? 4 : 2, MB = 4 / (NB / 2);
; #pragma unroll
;         for (int am = 0; am < NB; ++am) { const int ai = am / (NB / 2), m0 = (am % (NB / 2)) * MB;
;             f32x4 xo[4][2][2];
; #pragma unroll
;             for (int m = m0; m < m0 + MB; ++m) { const float* xr = Xs + (size_t)(row0 + ai * HALF + m * 16) * DM + col0;
; #pragma unroll
;                 for (int bj = 0; bj < 2; ++bj) { xo[m][bj][0] = *(const f32x4*)(xr + bj * HALF); xo[m][bj][1] = *(const f32x4*)(xr + bj * HALF + 4); } }
; #pragma unroll
;             for (int m = m0; m < m0 + MB; ++m) { const int row = row0 + ai * HALF + m * 16; float ss = 0.f;
;                 float* xr = X + (size_t)row * DM + col0; bf16_t* xb = XB + (size_t)row * ALD + col0;
; #pragma unroll
;                 for (int bj = 0; bj < 2; ++bj) { f32x4 x0 = xo[m][bj][0], x1 = xo[m][bj][1];
;                     if (HB) { x0 += (acc[ai][bj][m][0] + bv[bj][0]) * sv[bj][0]; x1 += (acc[ai][bj][m][1] + bv[bj][1]) * sv[bj][1]; } else { x0 += acc[ai][bj][m][0]; x1 += acc[ai][bj][m][1]; }
;                     *(f32x4*)(xr + bj * HALF) = x0; *(f32x4*)(xr + bj * HALF + 4) = x1;
	s_add_u32 s6, s50, 0x40000
	s_addc_u32 s7, s51, 0
	s_add_i32 s48, s48, s25
	v_lshl_add_u64 v[218:219], s[6:7], 0, v[138:139]
	s_mov_b32 m0, s48
	ds_read_b128 v[164:167], v245 offset:49152
	ds_read_b128 v[168:171], v245 offset:50176
	ds_read_b128 v[172:175], v245 offset:51200
	ds_read_b128 v[176:179], v245 offset:52224
	ds_read_b128 v[180:183], v245 offset:53248
	ds_read_b128 v[184:187], v245 offset:54272
	ds_read_b128 v[188:191], v245 offset:55296
	ds_read_b128 v[214:217], v245 offset:56320
	global_load_lds_dwordx4 v[218:219], off
	s_add_i32 m0, s48, 0x2000
	v_lshl_add_u64 v[218:219], s[6:7], 0, v[136:137]
	s_add_u32 s6, s50, 0x42000
	s_addc_u32 s7, s51, 0
	s_add_i32 s48, s49, s25
	global_load_lds_dwordx4 v[218:219], off
	v_lshl_add_u64 v[218:219], s[6:7], 0, v[138:139]
	s_mov_b32 m0, s48
	v_lshl_add_u64 v[198:199], v[198:199], 0, s[36:37]
	global_load_lds_dwordx4 v[218:219], off
	v_lshl_add_u64 v[218:219], s[6:7], 0, v[136:137]
	s_add_i32 m0, s48, 0x2000
	s_nop 0
	global_load_lds_dwordx4 v[218:219], off
	s_mov_b32 m0, s57
	s_nop 0
	global_load_lds_dwordx4 v[198:199], off
	v_lshl_add_u64 v[198:199], v[200:201], 0, s[36:37]
	s_mov_b32 m0, s58
	s_nop 0
	global_load_lds_dwordx4 v[198:199], off
	s_waitcnt vmcnt(9)
	s_waitcnt lgkmcnt(0)
	s_barrier
	s_setprio 1
	s_waitcnt lgkmcnt(0)
	v_mfma_f32_16x16x32_bf16 v[60:63], v[128:131], v[164:167], v[60:63]
	v_mfma_f32_16x16x32_bf16 v[56:59], v[140:143], v[164:167], v[56:59]
	v_mfma_f32_16x16x32_bf16 v[44:47], v[128:131], v[172:175], v[44:47]
	v_mfma_f32_16x16x32_bf16 v[40:43], v[140:143], v[172:175], v[40:43]
	v_mfma_f32_16x16x32_bf16 v[28:31], v[128:131], v[180:183], v[28:31]
	v_mfma_f32_16x16x32_bf16 v[24:27], v[140:143], v[180:183], v[24:27]
	v_mfma_f32_16x16x32_bf16 v[12:15], v[128:131], v[188:191], v[12:15]
	v_mfma_f32_16x16x32_bf16 v[8:11], v[140:143], v[188:191], v[8:11]
	v_mfma_f32_16x16x32_bf16 v[60:63], v[132:135], v[168:171], v[60:63]
	v_mfma_f32_16x16x32_bf16 v[56:59], v[144:147], v[168:171], v[56:59]
	v_mfma_f32_16x16x32_bf16 v[44:47], v[132:135], v[176:179], v[44:47]
	v_mfma_f32_16x16x32_bf16 v[40:43], v[144:147], v[176:179], v[40:43]
	v_mfma_f32_16x16x32_bf16 v[28:31], v[132:135], v[184:187], v[28:31]
	v_mfma_f32_16x16x32_bf16 v[24:27], v[144:147], v[184:187], v[24:27]
	v_mfma_f32_16x16x32_bf16 v[12:15], v[132:135], v[214:217], v[12:15]
	v_mfma_f32_16x16x32_bf16 v[8:11], v[144:147], v[214:217], v[8:11]
	s_setprio 0
	s_setprio 1
	v_mfma_f32_16x16x32_bf16 v[52:55], v[148:151], v[164:167], v[52:55]
	v_mfma_f32_16x16x32_bf16 v[48:51], v[156:159], v[164:167], v[48:51]
	v_mfma_f32_16x16x32_bf16 v[36:39], v[148:151], v[172:175], v[36:39]
	v_mfma_f32_16x16x32_bf16 v[32:35], v[156:159], v[172:175], v[32:35]
	v_mfma_f32_16x16x32_bf16 v[20:23], v[148:151], v[180:183], v[20:23]
	v_mfma_f32_16x16x32_bf16 v[16:19], v[156:159], v[180:183], v[16:19]
	v_mfma_f32_16x16x32_bf16 v[4:7], v[148:151], v[188:191], v[4:7]
	v_mfma_f32_16x16x32_bf16 v[0:3], v[156:159], v[188:191], v[0:3]
	v_mfma_f32_16x16x32_bf16 v[52:55], v[152:155], v[168:171], v[52:55]
	v_mfma_f32_16x16x32_bf16 v[48:51], v[160:163], v[168:171], v[48:51]
	v_mfma_f32_16x16x32_bf16 v[36:39], v[152:155], v[176:179], v[36:39]
	v_mfma_f32_16x16x32_bf16 v[32:35], v[160:163], v[176:179], v[32:35]
	v_mfma_f32_16x16x32_bf16 v[20:23], v[152:155], v[184:187], v[20:23]
	v_mfma_f32_16x16x32_bf16 v[16:19], v[160:163], v[184:187], v[16:19]
	v_mfma_f32_16x16x32_bf16 v[4:7], v[152:155], v[214:217], v[4:7]
	v_mfma_f32_16x16x32_bf16 v[0:3], v[160:163], v[214:217], v[0:3]
	s_setprio 0
	s_barrier
	s_add_i32 s79, s79, 2
	s_add_u32 s77, s77, 0x80000
	s_addc_u32 s78, s78, 0
	s_cmpk_gt_u32 s79, 0x55
	s_mov_b64 s[48:49], s[40:41]
	s_cbranch_scc0 .LBB0_927
	v_lshl_or_b32 v214, s74, 8, v244
	v_lshl_add_u32 v216, s75, 8, v197
	v_ashrrev_i32_e32 v215, 31, v214
	v_lshlrev_b64 v[198:199], 2, v[214:215]
	v_ashrrev_i32_e32 v217, 31, v216
	v_or_b32_e32 v226, 16, v216
	v_lshl_add_u64 v[218:219], s[82:83], 0, v[198:199]
	v_lshlrev_b64 v[200:201], 13, v[216:217]
	v_ashrrev_i32_e32 v227, 31, v226
	v_or_b32_e32 v222, 32, v216
	v_or_b32_e32 v220, 48, v216
	v_lshl_add_u64 v[128:129], v[218:219], 0, v[200:201]
	v_lshlrev_b64 v[230:231], 13, v[226:227]
	v_ashrrev_i32_e32 v223, 31, v222
	v_ashrrev_i32_e32 v221, 31, v220
	global_load_dwordx4 v[188:191], v[128:129], off offset:16
	global_load_dwordx4 v[246:249], v[128:129], off
	global_load_dwordx4 v[180:183], v[128:129], off offset:528
	global_load_dwordx4 v[184:187], v[128:129], off offset:512
	v_lshl_add_u64 v[128:129], v[218:219], 0, v[230:231]
	v_lshlrev_b64 v[228:229], 13, v[222:223]
	v_lshlrev_b64 v[224:225], 13, v[220:221]
	global_load_dwordx4 v[172:175], v[128:129], off offset:16
	global_load_dwordx4 v[176:179], v[128:129], off
	global_load_dwordx4 v[164:167], v[128:129], off offset:528
	global_load_dwordx4 v[168:171], v[128:129], off offset:512
	v_lshl_add_u64 v[128:129], v[218:219], 0, v[228:229]
	v_lshl_add_u64 v[132:133], v[218:219], 0, v[224:225]
	global_load_dwordx4 v[156:159], v[128:129], off offset:16
	global_load_dwordx4 v[160:163], v[128:129], off
	global_load_dwordx4 v[148:151], v[128:129], off offset:528
	global_load_dwordx4 v[152:155], v[128:129], off offset:512
	global_load_dwordx4 v[140:143], v[132:133], off offset:16
	global_load_dwordx4 v[144:147], v[132:133], off
	s_nop 0
	global_load_dwordx4 v[128:131], v[132:133], off offset:528
	s_nop 0
	global_load_dwordx4 v[132:135], v[132:133], off offset:512
	v_lshl_add_u64 v[200:201], s[82:83], 0, v[200:201]
	v_lshl_add_u64 v[234:235], v[200:201], 0, v[198:199]
	v_mov_b64_e32 v[198:199], s[4:5]
	v_mad_i64_i32 v[198:199], s[6:7], v216, s66, v[198:199]
	v_lshl_add_u64 v[232:233], v[214:215], 1, v[198:199]
	s_and_b64 vcc, exec, s[28:29]
	s_waitcnt vmcnt(12)
	v_pk_add_f32 v[122:123], v[122:123], v[190:191]
	v_pk_add_f32 v[126:127], v[126:127], v[248:249]
	v_pk_add_f32 v[124:125], v[124:125], v[246:247]
	v_pk_add_f32 v[120:121], v[120:121], v[188:189]
	global_store_dwordx4 v[234:235], v[124:127], off
	global_store_dwordx4 v[234:235], v[120:123], off offset:16
	v_cvt_pk_bf16_f32 v188, v124, v125
	v_cvt_pk_bf16_f32 v189, v126, v127
	v_cvt_pk_bf16_f32 v190, v120, v121
	v_cvt_pk_bf16_f32 v191, v122, v123
	s_cbranch_vccz .LBB0_930
	global_store_dwordx4 v[232:233], v[188:191], off
